# P7 processes its second panel group first (the HB panels P6 wrote last) and P8 keeps its original order (so it again starts with the ACT panels P7 wrote last); P1/P7 weight-block rotation kept
# speedup vs baseline: 1.0282x; 1.0035x over previous
;     __device__ __forceinline__ void tile(int L, int& pm, int& pn) const {
;         const unsigned w = (unsigned)(L & 7) * (2u * fnig) + (unsigned)(L >> 3), gid = __umulhi(w, fmagic), rem = w - gid * fnig; pm = (int)(gid * WGM + (rem & 7u)); pn = (int)(rem >> 3);
;     }
; __global__ void __launch_bounds__(512, 2) layer_fwd(Args args) {
;     ...
;     if (IN(7)) {
;         pg8::Sched S; S.A0 = (const char*)(ws + WS_HB); S.B0 = (const char*)(ws + WS_WUP); S.A1 = S.A0; S.B1 = S.B0;
;         S.nM0 = M / 256; S.nN0 = 16; S.n0 = S.nM0 * 16; S.n1 = 0; S.G = F.G; S.c = vb_; S.tstep = (size_t)256 * D * 2; S.nrep = NREP(7); S.prep();
;         pg8::EpiScale<1> E{(bf16_t*)(ws + WS_ACT), FF, ss3};
;         pg8::gemm_phase<pg8::EpiScale<1>, true, true>(F.lds, D, S, E);
;     }
.LBB0_1078:
	s_cmp_lt_i32 s82, 8
	s_cselect_b64 s[6:7], -1, 0
	s_and_b64 s[2:3], s[6:7], s[2:3]
	s_andn2_b64 vcc, exec, s[2:3]
	s_cbranch_vccnz .LBB0_1095
	s_cmpk_gt_i32 s52, 0x7ff
	v_readfirstlane_b32 s16, v228
	s_cbranch_scc1 .LBB0_1095
	v_lshrrev_b32_e32 v0, 5, v228
	v_lshrrev_b32_e32 v2, 1, v228
	v_and_b32_e32 v0, 4, v0
	s_waitcnt lgkmcnt(0)
	v_bfe_u32 v1, v228, 2, 2
	v_and_b32_e32 v2, 24, v2
	v_or3_b32 v0, v0, v1, v2
	v_lshlrev_b32_e32 v1, 4, v228
	v_add_u32_e32 v8, 0x2000, v1
	v_lshrrev_b32_e32 v2, 7, v8
	s_movk_i32 s6, 0xe0
	v_and_b32_e32 v4, 32, v228
	v_and_or_b32 v3, v2, s6, v0
	v_bitop3_b32 v9, v1, v4, 48 bitop3:0x6c
	v_and_b32_e32 v10, 64, v228
	v_bfe_u32 v11, v228, 2, 4
	s_movk_i32 s6, 0xf0
	s_add_u32 s48, s92, 0x3000000
	v_or_b32_e32 v1, v9, v10
	v_and_or_b32 v2, v2, s6, v11
	s_addc_u32 s49, s93, 0
	v_lshl_or_b32 v130, v2, 11, v1
	v_lshrrev_b32_e32 v2, 3, v228
	s_movk_i32 s6, 0x60
	s_add_u32 s50, s92, 0xd80000
	v_and_or_b32 v0, v2, s6, v0
	s_movk_i32 s6, 0x70
	s_addc_u32 s51, s93, 0
	v_lshl_or_b32 v132, v0, 11, v1
	v_and_or_b32 v0, v2, s6, v11
	s_lshl_b32 s6, s52, 8
	s_and_b32 s6, s6, 0x700
	s_ashr_i32 s7, s52, 3
	s_add_i32 s6, s6, s7
	s_lshr_b32 s6, s6, 4
	s_and_b32 s6, s6, 0xffffff8
	s_and_b32 s8, s7, 7
	s_lshr_b32 s14, s16, 6
	s_or_b32 s6, s6, s8
	s_xor_b32 s6, s6, 8
	s_bfe_u32 s71, s7, 0x40003
	s_and_b32 s98, s52, 3
	s_lshl_b32 s98, s98, 2
	s_add_i32 s71, s71, s98
	s_and_b32 s71, s71, 15
	s_mov_b32 s7, 0
	s_lshr_b32 s15, s16, 8
	s_lshl_b32 s53, s14, 10
	s_lshl_b64 s[8:9], s[6:7], 19
	s_lshl_b32 s10, s71, 19
	s_add_u32 s44, s50, s10
	s_addc_u32 s45, s51, 0
	s_add_i32 s54, s53, 0
	s_add_i32 m0, s54, 0x10000
	v_lshl_or_b32 v128, v3, 11, v1
	global_load_lds_dwordx4 v132, s[44:45]
	s_add_i32 m0, s54, 0x12000
	s_add_u32 s10, s44, 0x40000
	global_load_lds_dwordx4 v128, s[44:45]
	s_addc_u32 s11, s45, 0
	s_add_i32 m0, s54, 0x14000
	v_lshl_or_b32 v134, v0, 11, v1
	global_load_lds_dwordx4 v132, s[10:11]
	s_add_i32 m0, s54, 0x16000
	s_add_u32 s42, s48, s8
	s_addc_u32 s43, s49, s9
	s_add_i32 s55, s54, 0x2000
	global_load_lds_dwordx4 v128, s[10:11]
	s_mov_b32 m0, s54
	s_add_u32 s8, s42, 0x40000
	global_load_lds_dwordx4 v134, s[42:43]
	s_mov_b32 m0, s55
	s_addc_u32 s9, s43, 0
	s_add_i32 s56, s54, 0x4000
	global_load_lds_dwordx4 v130, s[42:43]
	s_mov_b32 m0, s56
	s_add_i32 s57, s54, 0x6000
	global_load_lds_dwordx4 v134, s[8:9]
	s_mov_b32 m0, s57
	v_mov_b32_e32 v133, 0
	global_load_lds_dwordx4 v130, s[8:9]
	v_mov_b32_e32 v129, v133
	v_mov_b32_e32 v135, v133
	v_mov_b32_e32 v131, v133
	s_cmp_eq_u32 s15, 1
	v_lshl_add_u64 v[6:7], s[44:45], 0, v[132:133]
	v_lshl_add_u64 v[2:3], s[44:45], 0, v[128:129]
	s_mov_b64 s[8:9], 0x40000
	v_lshl_add_u64 v[0:1], s[42:43], 0, v[134:135]
	s_cselect_b64 s[10:11], -1, 0
	s_cmp_lg_u32 s15, 1
	v_lshl_add_u64 v[4:5], s[42:43], 0, v[130:131]
	s_cbranch_scc1 .LBB0_1082
	s_barrier

;     __device__ __forceinline__ void tile(int L, int& pm, int& pn) const {
;         const unsigned w = (unsigned)(L & 7) * (2u * fnig) + (unsigned)(L >> 3), gid = __umulhi(w, fmagic), rem = w - gid * fnig; pm = (int)(gid * WGM + (rem & 7u)); pn = (int)(rem >> 3);
;     }
;     __device__ __forceinline__ bool next(int i, Unit& u) const {
;         int L = i * G + c;
;         if (nrep > 1) { if (L < n0 * nrep) { const int pass = L / n0; tile(L - pass * n0, u.pm, u.pn); u.kind = (pass + 1 < nrep) ? 2 : 0; return true; } L -= n0 * (nrep - 1); }
;         if (L < n0) { tile(L, u.pm, u.pn); u.pn += pnoff; u.kind = 0; return true; }
.LBB0_1085:
	s_add_i32 s7, s7, 1
	s_mul_i32 s31, s7, s33
	s_add_i32 s31, s31, s52
	s_cmpk_lt_i32 s31, 0x800
	s_cselect_b64 s[38:39], -1, 0
	s_cmpk_gt_i32 s31, 0x7ff
	s_cbranch_scc1 .LBB0_1087
	s_lshl_b32 s30, s31, 8
	s_and_b32 s30, s30, 0x700
	s_ashr_i32 s31, s31, 3
	s_add_i32 s30, s30, s31
	s_lshr_b32 s30, s30, 4
	s_and_b32 s30, s30, 0xffffff8
	s_and_b32 s34, s31, 7
	s_or_b32 s30, s30, s34
	s_xor_b32 s30, s30, 8
	s_bfe_u32 s34, s31, 0x40003
	s_and_b32 s98, s52, 3
	s_lshl_b32 s98, s98, 2
	s_add_i32 s34, s34, s98
	s_and_b32 s34, s34, 15
